# sample in-projection: rope cos/sin fragment loaded once before the task loop (was twice per task behind vmcnt(0))
# baseline (speedup 1.0000x reference)
.LBB0_602:
	v_readlane_b32 s0, v254, 1
	v_readlane_b32 s1, v254, 2
	s_and_b64 vcc, exec, s[4:5]
	s_cbranch_vccnz .LBB0_618
	s_load_dwordx4 s[40:43], s[0:1], 0x70
	s_mov_b32 s4, -1
	v_readlane_b32 s5, v254, 0
	s_waitcnt lgkmcnt(0)
	v_lshrrev_b32_e32 v164, 2, v224
	v_and_b32_e32 v164, 12, v164
	v_bfe_u32 v165, v224, 6, 2
	v_lshl_or_b32 v164, v165, 4, v164
	v_lshlrev_b32_e32 v164, 2, v164
	v_lshlrev_b32_e32 v165, 8, v224
	v_and_b32_e32 v165, 0x700, v165
	v_or_b32_e32 v165, 0x80000, v165
	v_add_u32_e32 v164, v164, v165
	v_mov_b32_e32 v165, 0
	v_lshl_add_u64 v[164:165], s[42:43], 0, v[164:165]
	s_mov_b64 s[0:1], 0x4580800
	v_lshl_add_u64 v[166:167], v[164:165], 0, s[0:1]
	global_load_dwordx4 v[156:159], v[166:167], off
	s_mov_b64 s[0:1], 0x4500000
	v_lshl_add_u64 v[166:167], v[164:165], 0, s[0:1]
	global_load_dwordx4 v[160:163], v[166:167], off
	s_add_u32 s0, s40, s9
	s_addc_u32 s1, s41, s8
	s_add_u32 s2, s0, 0xccf0000
	s_addc_u32 s3, s1, 0
	s_branch .LBB0_605

.LBB0_609:
	s_cmpk_gt_u32 s0, 0xff
	s_waitcnt lgkmcnt(0)
	s_barrier
	s_cbranch_scc1 .LBB0_604
	v_lshrrev_b32_e32 v18, 2, v16
	s_lshr_b32 s0, s0, 6
	v_and_b32_e32 v18, 12, v18
	v_lshl_or_b32 v22, s0, 4, v18
	s_lshl_b32 s0, s0, 12
	s_add_i32 s0, s0, 0
	v_lshl_add_u32 v24, v17, 4, s0
	ds_read_b128 v[26:29], v24
	v_lshlrev_b32_e32 v17, 8, v16
	s_add_i32 s8, s7, -4
	v_and_b32_e32 v17, 0x700, v17
	s_cmp_lt_u32 s8, 8
	s_waitcnt lgkmcnt(0)
	v_pk_add_f32 v[10:11], v[10:11], v[28:29]
	v_pk_add_f32 v[8:9], v[8:9], v[26:27]
	ds_read_b128 v[26:29], v24 offset:1024
	v_or_b32_e32 v18, 0x80000, v17
	v_mov_b32_e32 v19, v197
	s_cselect_b64 s[0:1], -1, 0
	s_cmp_gt_u32 s7, 7
	v_lshlrev_b32_e32 v196, 2, v22
	v_lshl_add_u64 v[18:19], s[10:11], 0, v[18:19]
	s_cselect_b64 s[38:39], -1, 0
	s_cmp_gt_u32 s8, 7
	v_lshl_add_u64 v[20:21], v[18:19], 0, v[196:197]
	s_mov_b64 s[8:9], 0x4500000
	v_lshl_add_u64 v[18:19], v[20:21], 0, s[8:9]
	s_mov_b64 s[8:9], 0x4580800
	v_lshl_add_u64 v[20:21], v[20:21], 0, s[8:9]
	s_waitcnt lgkmcnt(0)
	v_pk_add_f32 v[14:15], v[14:15], v[28:29]
	v_pk_add_f32 v[12:13], v[12:13], v[26:27]
	s_cbranch_scc1 .LBB0_612
	v_pk_mul_f32 v[34:35], v[14:15], v[158:159]
	v_pk_mul_f32 v[36:37], v[12:13], v[156:157]
	v_pk_mul_f32 v[28:29], v[10:11], v[158:159]
	v_pk_mul_f32 v[26:27], v[8:9], v[156:157]
	v_pk_fma_f32 v[10:11], v[10:11], v[162:163], v[34:35] neg_lo:[0,0,1] neg_hi:[0,0,1]
	v_pk_fma_f32 v[8:9], v[8:9], v[160:161], v[36:37] neg_lo:[0,0,1] neg_hi:[0,0,1]
	v_pk_fma_f32 v[14:15], v[14:15], v[162:163], v[28:29]
	v_pk_fma_f32 v[12:13], v[12:13], v[160:161], v[26:27]
	v_pk_mul_f32 v[26:27], v[8:9], s[14:15] op_sel_hi:[1,0]
	v_pk_mul_f32 v[28:29], v[10:11], s[14:15] op_sel_hi:[1,0]
	v_pk_mul_f32 v[30:31], v[12:13], s[14:15] op_sel_hi:[1,0]
	v_pk_mul_f32 v[32:33], v[14:15], s[14:15] op_sel_hi:[1,0]
	v_cndmask_b32_e64 v11, v11, v29, s[38:39]
	v_cndmask_b32_e64 v10, v10, v28, s[38:39]
	v_cndmask_b32_e64 v9, v9, v27, s[38:39]
	v_cndmask_b32_e64 v8, v8, v26, s[38:39]
	v_cndmask_b32_e64 v15, v15, v33, s[38:39]
	v_cndmask_b32_e64 v14, v14, v32, s[38:39]
	v_cndmask_b32_e64 v13, v13, v31, s[38:39]
	v_cndmask_b32_e64 v12, v12, v30, s[38:39]

.LBB0_614:
	ds_read_b128 v[8:11], v24 offset:2048
	s_andn2_b64 vcc, exec, s[0:1]
	s_waitcnt lgkmcnt(0)
	v_pk_add_f32 v[6:7], v[6:7], v[10:11]
	v_pk_add_f32 v[4:5], v[4:5], v[8:9]
	ds_read_b128 v[8:11], v24 offset:3072
	s_waitcnt lgkmcnt(0)
	v_pk_add_f32 v[2:3], v[2:3], v[10:11]
	v_pk_add_f32 v[0:1], v[0:1], v[8:9]
	s_cbranch_vccnz .LBB0_616
	v_pk_mul_f32 v[18:19], v[2:3], v[158:159]
	v_pk_mul_f32 v[20:21], v[0:1], v[156:157]
	v_pk_mul_f32 v[10:11], v[6:7], v[158:159]
	v_pk_mul_f32 v[8:9], v[4:5], v[156:157]
	v_pk_fma_f32 v[6:7], v[6:7], v[162:163], v[18:19] neg_lo:[0,0,1] neg_hi:[0,0,1]
	v_pk_fma_f32 v[4:5], v[4:5], v[160:161], v[20:21] neg_lo:[0,0,1] neg_hi:[0,0,1]
	v_pk_fma_f32 v[2:3], v[2:3], v[162:163], v[10:11]
	v_pk_fma_f32 v[0:1], v[0:1], v[160:161], v[8:9]
	v_pk_mul_f32 v[8:9], v[4:5], s[14:15] op_sel_hi:[1,0]
	v_pk_mul_f32 v[10:11], v[6:7], s[14:15] op_sel_hi:[1,0]
	v_pk_mul_f32 v[12:13], v[0:1], s[14:15] op_sel_hi:[1,0]
	v_pk_mul_f32 v[14:15], v[2:3], s[14:15] op_sel_hi:[1,0]
	v_cndmask_b32_e64 v7, v7, v11, s[38:39]
	v_cndmask_b32_e64 v6, v6, v10, s[38:39]
	v_cndmask_b32_e64 v5, v5, v9, s[38:39]
	v_cndmask_b32_e64 v4, v4, v8, s[38:39]
	v_cndmask_b32_e64 v3, v3, v15, s[38:39]
	v_cndmask_b32_e64 v2, v2, v14, s[38:39]
	v_cndmask_b32_e64 v1, v1, v13, s[38:39]
	v_cndmask_b32_e64 v0, v0, v12, s[38:39]
